# attention main loop: row-max tree rewritten as two v_max3 chains (16 VALU instead of 19/20 per step, no self-max canonicalisation, the accumulator written last is read last so the s_nop in front of it
# speedup vs baseline: 1.0047x; 1.0047x over previous
.LBB0_1547:
	v_add_u32_e32 v0, s8, v221
	ds_read_b64_tr_b16 v[192:193], v0 offset:24576
	ds_read_b64_tr_b16 v[194:195], v0 offset:25088
	s_waitcnt lgkmcnt(9)
	v_mfma_f32_32x32x16_bf16 v[112:127], v[188:191], v[148:151], v[48:63]
	v_add_f32_e32 v2, v80, v81
	v_add_f32_e32 v2, v82, v2
	v_add_f32_e32 v2, v83, v2
	v_add_f32_e32 v2, v84, v2
	v_add_f32_e32 v2, v85, v2
	v_cvt_pk_bf16_f32 v156, v80, v81
	v_cvt_pk_bf16_f32 v157, v82, v83
	ds_read_b64_tr_b16 v[188:189], v0 offset:28672
	ds_read_b64_tr_b16 v[190:191], v0 offset:29184
	s_waitcnt lgkmcnt(10)
	v_mfma_f32_32x32x16_bf16 v[96:111], v[184:187], v[148:151], v[48:63]
	v_add_f32_e32 v2, v86, v2
	v_add_f32_e32 v2, v87, v2
	v_add_f32_e32 v2, v88, v2
	v_add_f32_e32 v2, v89, v2
	v_cvt_pk_bf16_f32 v158, v84, v85
	v_cvt_pk_bf16_f32 v159, v86, v87
	ds_read_b64_tr_b16 v[184:185], v0 offset:25600
	ds_read_b64_tr_b16 v[186:187], v0 offset:26112
	s_waitcnt lgkmcnt(11)
	v_mfma_f32_32x32x16_bf16 v[112:127], v[180:183], v[140:143], v[112:127]
	v_add_f32_e32 v2, v90, v2
	v_add_f32_e32 v2, v91, v2
	v_add_f32_e32 v2, v92, v2
	v_add_f32_e32 v2, v93, v2
	v_cvt_pk_bf16_f32 v152, v88, v89
	v_cvt_pk_bf16_f32 v153, v90, v91
	ds_read_b64_tr_b16 v[84:85], v0 offset:29696
	ds_read_b64_tr_b16 v[86:87], v0 offset:30208
	s_waitcnt lgkmcnt(12)
	v_mfma_f32_32x32x16_bf16 v[96:111], v[176:179], v[140:143], v[96:111]
	v_add_f32_e32 v2, v94, v2
	v_add_f32_e32 v2, v95, v2
	v_add_f32_e32 v2, v64, v2
	v_add_f32_e32 v2, v65, v2
	v_cvt_pk_bf16_f32 v154, v92, v93
	v_cvt_pk_bf16_f32 v155, v94, v95
	ds_read_b64_tr_b16 v[80:81], v0 offset:26624
	ds_read_b64_tr_b16 v[82:83], v0 offset:27136
	s_waitcnt lgkmcnt(13)
	v_mfma_f32_32x32x16_bf16 v[112:127], v[172:175], v[132:135], v[112:127]
	v_add_f32_e32 v2, v66, v2
	v_add_f32_e32 v2, v67, v2
	v_add_f32_e32 v2, v68, v2
	v_add_f32_e32 v2, v69, v2
	v_cvt_pk_bf16_f32 v144, v64, v65
	v_cvt_pk_bf16_f32 v145, v66, v67
	ds_read_b64_tr_b16 v[10:11], v0 offset:30720
	ds_read_b64_tr_b16 v[12:13], v0 offset:31232
	s_waitcnt lgkmcnt(14)
	v_mfma_f32_32x32x16_bf16 v[96:111], v[168:171], v[132:135], v[96:111]
	v_add_f32_e32 v2, v70, v2
	v_add_f32_e32 v2, v71, v2
	v_add_f32_e32 v2, v72, v2
	v_add_f32_e32 v2, v73, v2
	v_cvt_pk_bf16_f32 v146, v68, v69
	v_cvt_pk_bf16_f32 v147, v70, v71
	ds_read_b64_tr_b16 v[6:7], v0 offset:27648
	ds_read_b64_tr_b16 v[8:9], v0 offset:28160
	s_waitcnt lgkmcnt(14)
	v_mfma_f32_32x32x16_bf16 v[112:127], v[164:167], v[128:131], v[112:127]
	v_add_f32_e32 v2, v74, v2
	v_add_f32_e32 v2, v75, v2
	v_add_f32_e32 v2, v76, v2
	v_add_f32_e32 v14, v77, v2
	v_cvt_pk_bf16_f32 v136, v72, v73
	v_cvt_pk_bf16_f32 v137, v74, v75
	ds_read_b64_tr_b16 v[2:3], v0 offset:31744
	ds_read_b64_tr_b16 v[4:5], v0 offset:32256
	v_mfma_f32_32x32x16_bf16 v[96:111], v[160:163], v[128:131], v[96:111]
	v_add_f32_e32 v0, v78, v14
	v_add_f32_e32 v0, v79, v0
	v_cvt_pk_bf16_f32 v138, v76, v77
	v_cvt_pk_bf16_f32 v139, v78, v79
	v_lshl_add_u64 v[14:15], v[202:203], 0, s[26:27]
	s_add_i32 s8, s40, s46
	s_mov_b32 s9, m0
	s_mov_b32 m0, s8
	s_nop 0
	global_load_lds_dwordx4 v[14:15], off
	s_mov_b32 m0, s9
	v_lshl_add_u64 v[14:15], v[200:201], 0, s[26:27]
	s_add_i32 s8, s38, s47
	s_mov_b32 s9, m0
	s_mov_b32 m0, s8
	s_nop 0
	global_load_lds_dwordx4 v[14:15], off
	s_mov_b32 m0, s9
	v_max3_f32 v14, v112, v113, v114
	v_max3_f32 v15, v115, v116, v117
	v_max3_f32 v14, v14, v118, v119
	v_max3_f32 v15, v15, v120, v121
	v_max3_f32 v14, v14, v122, v123
	v_max3_f32 v15, v15, v124, v125
	v_max3_f32 v14, v14, v126, v127
	v_max3_f32 v15, v15, v96, v97
	v_max3_f32 v14, v14, v98, v99
	v_max3_f32 v15, v15, v100, v101
	v_max3_f32 v14, v14, v102, v103
	v_max3_f32 v15, v15, v104, v105
	v_max3_f32 v14, v14, v106, v107
	v_max3_f32 v15, v15, v108, v109
	v_max3_f32 v64, v14, v110, v111
	v_add_f32_e32 v14, v223, v0
	v_max_f32_e32 v0, v64, v15
	v_mov_b32_e32 v15, v0
	s_nop 1
	v_permlane32_swap_b32_e32 v0, v15
	v_max_f32_e32 v0, v0, v15
	v_cmp_lt_f32_e32 vcc, s53, v0
	s_cmp_lg_u64 vcc, 0
	s_cselect_b64 s[8:9], -1, 0
	s_cbranch_vccnz .LBB0_1555

.LBB0_1550:
	s_add_i32 s8, s38, 0x2000
	s_cmpk_lg_i32 s38, 0x4000
	s_cselect_b32 s13, s8, 0
	v_add_u32_e32 v4, s40, v221
	ds_read_b64_tr_b16 v[168:169], v4 offset:24576
	ds_read_b64_tr_b16 v[170:171], v4 offset:25088
	s_waitcnt lgkmcnt(9)
	v_mfma_f32_32x32x16_bf16 v[80:95], v[64:67], v[148:151], v[48:63]
	v_add_f32_e32 v2, v112, v113
	v_add_f32_e32 v2, v114, v2
	v_add_f32_e32 v2, v115, v2
	v_add_f32_e32 v2, v116, v2
	v_add_f32_e32 v2, v117, v2
	v_cvt_pk_bf16_f32 v156, v112, v113
	v_cvt_pk_bf16_f32 v157, v114, v115
	ds_read_b64_tr_b16 v[164:165], v4 offset:28672
	ds_read_b64_tr_b16 v[166:167], v4 offset:29184
	s_waitcnt lgkmcnt(10)
	v_mfma_f32_32x32x16_bf16 v[64:79], v[160:163], v[148:151], v[48:63]
	v_add_f32_e32 v2, v118, v2
	v_add_f32_e32 v2, v119, v2
	v_add_f32_e32 v2, v120, v2
	v_add_f32_e32 v2, v121, v2
	v_cvt_pk_bf16_f32 v158, v116, v117
	v_cvt_pk_bf16_f32 v159, v118, v119
	ds_read_b64_tr_b16 v[160:161], v4 offset:25600
	ds_read_b64_tr_b16 v[162:163], v4 offset:26112
	s_waitcnt lgkmcnt(11)
	v_mfma_f32_32x32x16_bf16 v[80:95], v[192:195], v[140:143], v[80:95]
	v_add_f32_e32 v2, v122, v2
	v_add_f32_e32 v2, v123, v2
	v_add_f32_e32 v2, v124, v2
	v_add_f32_e32 v2, v125, v2
	v_cvt_pk_bf16_f32 v152, v120, v121
	v_cvt_pk_bf16_f32 v153, v122, v123
	ds_read_b64_tr_b16 v[116:117], v4 offset:29696
	ds_read_b64_tr_b16 v[118:119], v4 offset:30208
	s_waitcnt lgkmcnt(12)
	v_mfma_f32_32x32x16_bf16 v[64:79], v[184:187], v[140:143], v[64:79]
	v_add_f32_e32 v2, v126, v2
	v_add_f32_e32 v2, v127, v2
	v_add_f32_e32 v2, v96, v2
	v_add_f32_e32 v2, v97, v2
	v_cvt_pk_bf16_f32 v154, v124, v125
	v_cvt_pk_bf16_f32 v155, v126, v127
	ds_read_b64_tr_b16 v[112:113], v4 offset:26624
	ds_read_b64_tr_b16 v[114:115], v4 offset:27136
	s_waitcnt lgkmcnt(13)
	v_mfma_f32_32x32x16_bf16 v[80:95], v[188:191], v[132:135], v[80:95]
	v_add_f32_e32 v2, v98, v2
	v_add_f32_e32 v2, v99, v2
	v_add_f32_e32 v2, v100, v2
	v_add_f32_e32 v2, v101, v2
	v_cvt_pk_bf16_f32 v144, v96, v97
	v_cvt_pk_bf16_f32 v145, v98, v99
	ds_read_b64_tr_b16 v[10:11], v4 offset:30720
	ds_read_b64_tr_b16 v[12:13], v4 offset:31232
	s_waitcnt lgkmcnt(14)
	v_mfma_f32_32x32x16_bf16 v[64:79], v[176:179], v[132:135], v[64:79]
	v_add_f32_e32 v2, v102, v2
	v_add_f32_e32 v2, v103, v2
	v_add_f32_e32 v2, v104, v2
	v_add_f32_e32 v2, v105, v2
	v_cvt_pk_bf16_f32 v146, v100, v101
	v_cvt_pk_bf16_f32 v147, v102, v103
	ds_read_b64_tr_b16 v[6:7], v4 offset:27648
	ds_read_b64_tr_b16 v[8:9], v4 offset:28160
	s_waitcnt lgkmcnt(14)
	v_mfma_f32_32x32x16_bf16 v[80:95], v[180:183], v[128:131], v[80:95]
	v_add_f32_e32 v2, v106, v2
	v_add_f32_e32 v2, v107, v2
	v_add_f32_e32 v2, v108, v2
	v_add_f32_e32 v15, v109, v2
	v_cvt_pk_bf16_f32 v136, v104, v105
	v_cvt_pk_bf16_f32 v137, v106, v107
	ds_read_b64_tr_b16 v[2:3], v4 offset:31744
	ds_read_b64_tr_b16 v[4:5], v4 offset:32256
	v_mfma_f32_32x32x16_bf16 v[64:79], v[172:175], v[128:131], v[64:79]
	v_add_f32_e32 v15, v110, v15
	v_add_f32_e32 v15, v111, v15
	v_cvt_pk_bf16_f32 v138, v108, v109
	v_cvt_pk_bf16_f32 v139, v110, v111
	v_max3_f32 v96, v80, v81, v82
	v_max3_f32 v97, v83, v84, v85
	v_max3_f32 v96, v96, v86, v87
	v_max3_f32 v97, v97, v88, v89
	v_max3_f32 v96, v96, v90, v91
	v_max3_f32 v97, v97, v92, v93
	v_max3_f32 v96, v96, v94, v95
	v_add_f32_e32 v223, v14, v15
	s_nop 0
	v_max3_f32 v97, v97, v64, v65
	v_max3_f32 v96, v96, v66, v67
	v_max3_f32 v97, v97, v68, v69
	v_max3_f32 v96, v96, v70, v71
	v_max3_f32 v97, v97, v72, v73
	v_max3_f32 v96, v96, v74, v75
	v_max3_f32 v97, v97, v76, v77
	v_max3_f32 v96, v96, v78, v79
	v_max_f32_e32 v14, v96, v97
	v_mov_b32_e32 v15, v14
	s_nop 1
	v_permlane32_swap_b32_e32 v14, v15
	s_add_i32 s8, s38, s46
	s_mov_b32 s9, m0
	s_mov_b32 m0, s8
	s_nop 0
	global_load_lds_dwordx4 v[202:203], off
	s_mov_b32 m0, s9
	v_max_f32_e32 v14, v14, v15
	s_add_i32 s8, s13, s47
	s_mov_b32 s9, m0
	s_mov_b32 m0, s8
	s_nop 0
	global_load_lds_dwordx4 v[200:201], off
	s_mov_b32 m0, s9
	v_cmp_lt_f32_e32 vcc, s53, v14
	s_cmp_lg_u64 vcc, 0
	s_cselect_b64 s[8:9], -1, 0
	s_cbranch_vccnz .LBB0_1558
